# ret_out epilogue: gate loads and GY stores paired into dwordx4 (row-per-lane 16-B segments -> 32-B) via permlane32_swap, 12 pair-loads in flight; on top of v84
# speedup vs baseline: 1.0199x; 1.0081x over previous
; __device__ __forceinline__ unsigned cvtpk(float lo, float hi) { return pg8::cvt_pk_bf16(lo, hi); }
;     ...
;         { R2_IDS const float rstd = 1.0f / sqrtf((ssp[32 * nt + r] + ssp[128 + 32 * nt + r]) * (1.0f / 512.0f) + RMS_EPS);
;           bf16* gp = GY + ((size_t)((bh >> 2) * SEQ + tq0 + 32 * nt + r)) * 2048 + h * 512 + 256 * eh + 4 * hh;
; #pragma unroll
;           for (int et = 0; et < 8; ++et)
; #pragma unroll
;               for (int i4 = 0; i4 < 4; ++i4) { bf16* p4 = gp + 32 * et + 8 * i4; const v2u gg = *(const v2u*)p4;
;                   v2u wv; wv.x = cvtpk(acc[et][4 * i4] * rstd * __uint_as_float(gg.x << 16), acc[et][4 * i4 + 1] * rstd * __uint_as_float(gg.x & 0xffff0000u));
;                   wv.y = cvtpk(acc[et][4 * i4 + 2] * rstd * __uint_as_float(gg.y << 16), acc[et][4 * i4 + 3] * rstd * __uint_as_float(gg.y & 0xffff0000u));
;                   if (!dry || rstd == 1.2345e38f) *(v2u*)p4 = wv; if (i4 == 3 && (et & 1)) asm volatile("" ::: "memory"); } }
.LBB0_717:
	s_or_b64 exec, exec, s[6:7]
	s_lshl_b32 s6, s36, 5
	s_and_b32 s6, s6, 0xffffe000
	v_mov_b32_e32 v52, v33
	s_add_i32 s5, s5, s6
	s_waitcnt lgkmcnt(0)
	s_barrier
	s_or_b32 s5, s5, s47
	s_waitcnt vmcnt(2)
	v_and_b32_e32 v56, 31, v52
	v_or_b32_e32 v50, s5, v56
	v_ashrrev_i32_e32 v51, 31, v50
	v_lshlrev_b64 v[50:51], 12, v[50:51]
	v_lshl_add_u64 v[50:51], s[28:29], 0, v[50:51]
	s_lshl_b32 s94, s4, 10
	v_lshl_add_u64 v[50:51], v[50:51], 0, s[94:95]
	v_lshrrev_b32_e32 v52, 2, v52
	v_lshl_add_u64 v[50:51], s[30:31], 1, v[50:51]
	v_and_b32_e32 v52, 8, v52
	v_lshlrev_b32_e32 v52, 1, v52
	v_mov_b32_e32 v53, v32
	v_lshl_add_u64 v[50:51], v[50:51], 0, v[52:53]
	global_load_dwordx4 v[82:85], v[50:51], off
	global_load_dwordx4 v[86:89], v[50:51], off offset:32
	global_load_dwordx4 v[90:93], v[50:51], off offset:64
	global_load_dwordx4 v[204:207], v[50:51], off offset:96
	global_load_dwordx4 v[208:211], v[50:51], off offset:128
	global_load_dwordx4 v[212:215], v[50:51], off offset:160
	global_load_dwordx4 v[216:219], v[50:51], off offset:192
	global_load_dwordx4 v[220:223], v[50:51], off offset:224
	global_load_dwordx4 v[224:227], v[50:51], off offset:256
	global_load_dwordx4 v[238:241], v[50:51], off offset:288
	global_load_dwordx4 v[242:245], v[50:51], off offset:320
	global_load_dwordx4 v[246:249], v[50:51], off offset:352
	v_lshl_add_u32 v52, v56, 2, s50
	ds_read2st64_b32 v[52:53], v52 offset1:2
	s_add_i32 s36, s36, s48
	s_cmpk_lt_i32 s36, 0x200
	s_waitcnt lgkmcnt(0)
	v_add_f32_e32 v52, v52, v53
	v_fmamk_f32 v52, v52, 0x3b000000, v231
	v_mul_f32_e32 v53, 0x4f800000, v52
	v_cmp_gt_f32_e32 vcc, s73, v52
	s_nop 1
	v_cndmask_b32_e32 v52, v52, v53, vcc
	v_sqrt_f32_e32 v53, v52
	s_nop 0
	v_add_u32_e32 v56, -1, v53
	v_add_u32_e32 v57, 1, v53
	v_fma_f32 v58, -v56, v53, v52
	v_fma_f32 v59, -v57, v53, v52
	v_cmp_ge_f32_e64 s[40:41], 0, v58
	s_nop 1
	v_cndmask_b32_e64 v53, v53, v56, s[40:41]
	v_cmp_lt_f32_e64 s[40:41], 0, v59
	s_nop 1
	v_cndmask_b32_e64 v53, v53, v57, s[40:41]
	v_mul_f32_e32 v56, 0x37800000, v53
	v_cndmask_b32_e32 v53, v53, v56, vcc
	v_cmp_class_f32_e32 vcc, v52, v232
	s_nop 1
	v_cndmask_b32_e32 v52, v53, v52, vcc
	v_div_scale_f32 v53, s[4:5], v52, v52, 1.0
	v_rcp_f32_e32 v56, v53
	v_div_scale_f32 v57, vcc, 1.0, v52, 1.0
	v_fma_f32 v58, -v53, v56, 1.0
	v_fmac_f32_e32 v56, v58, v56
	v_mul_f32_e32 v58, v57, v56
	v_fma_f32 v59, -v53, v58, v57
	v_fmac_f32_e32 v58, v59, v56
	v_fma_f32 v53, -v53, v58, v57
	v_div_fmas_f32 v53, v53, v56, v58
	v_div_fixup_f32 v52, v53, v52, 1.0
	s_waitcnt vmcnt(11)
	v_permlane32_swap_b32_e32 v82, v84
	v_permlane32_swap_b32_e32 v83, v85
	v_lshlrev_b32_e32 v57, 16, v82
	v_and_b32_e32 v58, 0xffff0000, v82
	v_lshlrev_b32_e32 v59, 16, v83
	v_and_b32_e32 v60, 0xffff0000, v83
	v_mul_f32_e32 v53, v178, v52
	v_mul_f32_e32 v54, v179, v52
	v_mul_f32_e32 v55, v180, v52
	v_mul_f32_e32 v56, v181, v52
	v_mul_f32_e32 v53, v53, v57
	v_mul_f32_e32 v54, v54, v58
	v_mul_f32_e32 v55, v55, v59
	v_mul_f32_e32 v56, v56, v60
	v_cvt_pk_bf16_f32 v250, v53, v54
	v_cvt_pk_bf16_f32 v251, v55, v56
	v_lshlrev_b32_e32 v57, 16, v84
	v_and_b32_e32 v58, 0xffff0000, v84
	v_lshlrev_b32_e32 v59, 16, v85
	v_and_b32_e32 v60, 0xffff0000, v85
	v_mul_f32_e32 v53, v182, v52
	v_mul_f32_e32 v54, v183, v52
	v_mul_f32_e32 v55, v184, v52
	v_mul_f32_e32 v56, v185, v52
	v_mul_f32_e32 v53, v53, v57
	v_mul_f32_e32 v54, v54, v58
	v_mul_f32_e32 v55, v55, v59
	v_mul_f32_e32 v56, v56, v60
	v_cvt_pk_bf16_f32 v252, v53, v54
	v_cvt_pk_bf16_f32 v253, v55, v56
	s_nop 1
	v_permlane32_swap_b32_e32 v250, v252
	v_permlane32_swap_b32_e32 v251, v253
	global_store_dwordx4 v[50:51], v[250:253], off
	global_load_dwordx4 v[82:85], v[50:51], off offset:384
	s_waitcnt vmcnt(12)
	v_permlane32_swap_b32_e32 v86, v88
	v_permlane32_swap_b32_e32 v87, v89
	v_lshlrev_b32_e32 v57, 16, v86
	v_and_b32_e32 v58, 0xffff0000, v86
	v_lshlrev_b32_e32 v59, 16, v87
	v_and_b32_e32 v60, 0xffff0000, v87
	v_mul_f32_e32 v53, v186, v52
	v_mul_f32_e32 v54, v187, v52
	v_mul_f32_e32 v55, v188, v52
	v_mul_f32_e32 v56, v189, v52
	v_mul_f32_e32 v53, v53, v57
	v_mul_f32_e32 v54, v54, v58
	v_mul_f32_e32 v55, v55, v59
	v_mul_f32_e32 v56, v56, v60
	v_cvt_pk_bf16_f32 v250, v53, v54
	v_cvt_pk_bf16_f32 v251, v55, v56
	v_lshlrev_b32_e32 v57, 16, v88
	v_and_b32_e32 v58, 0xffff0000, v88
	v_lshlrev_b32_e32 v59, 16, v89
	v_and_b32_e32 v60, 0xffff0000, v89
	v_mul_f32_e32 v53, v190, v52
	v_mul_f32_e32 v54, v191, v52
	v_mul_f32_e32 v55, v192, v52
	v_mul_f32_e32 v56, v193, v52
	v_mul_f32_e32 v53, v53, v57
	v_mul_f32_e32 v54, v54, v58
	v_mul_f32_e32 v55, v55, v59
	v_mul_f32_e32 v56, v56, v60
	v_cvt_pk_bf16_f32 v252, v53, v54
	v_cvt_pk_bf16_f32 v253, v55, v56
	s_nop 1
	v_permlane32_swap_b32_e32 v250, v252
	v_permlane32_swap_b32_e32 v251, v253
	global_store_dwordx4 v[50:51], v[250:253], off offset:32
	global_load_dwordx4 v[86:89], v[50:51], off offset:416
	s_waitcnt vmcnt(13)
	v_permlane32_swap_b32_e32 v90, v92
	v_permlane32_swap_b32_e32 v91, v93
	v_lshlrev_b32_e32 v57, 16, v90
	v_and_b32_e32 v58, 0xffff0000, v90
	v_lshlrev_b32_e32 v59, 16, v91
	v_and_b32_e32 v60, 0xffff0000, v91
	v_mul_f32_e32 v53, v162, v52
	v_mul_f32_e32 v54, v163, v52
	v_mul_f32_e32 v55, v164, v52
	v_mul_f32_e32 v56, v165, v52
	v_mul_f32_e32 v53, v53, v57
	v_mul_f32_e32 v54, v54, v58
	v_mul_f32_e32 v55, v55, v59
	v_mul_f32_e32 v56, v56, v60
	v_cvt_pk_bf16_f32 v250, v53, v54
	v_cvt_pk_bf16_f32 v251, v55, v56
	v_lshlrev_b32_e32 v57, 16, v92
	v_and_b32_e32 v58, 0xffff0000, v92
	v_lshlrev_b32_e32 v59, 16, v93
	v_and_b32_e32 v60, 0xffff0000, v93
	v_mul_f32_e32 v53, v166, v52
	v_mul_f32_e32 v54, v167, v52
	v_mul_f32_e32 v55, v168, v52
	v_mul_f32_e32 v56, v169, v52
	v_mul_f32_e32 v53, v53, v57
	v_mul_f32_e32 v54, v54, v58
	v_mul_f32_e32 v55, v55, v59
	v_mul_f32_e32 v56, v56, v60
	v_cvt_pk_bf16_f32 v252, v53, v54
	v_cvt_pk_bf16_f32 v253, v55, v56
	s_nop 1
	v_permlane32_swap_b32_e32 v250, v252
	v_permlane32_swap_b32_e32 v251, v253
	global_store_dwordx4 v[50:51], v[250:253], off offset:64
	global_load_dwordx4 v[90:93], v[50:51], off offset:448
	s_waitcnt vmcnt(14)
; __device__ __forceinline__ unsigned cvtpk(float lo, float hi) { return pg8::cvt_pk_bf16(lo, hi); }
;     ...
;               for (int i4 = 0; i4 < 4; ++i4) { bf16* p4 = gp + 32 * et + 8 * i4; const v2u gg = *(const v2u*)p4;
;                   v2u wv; wv.x = cvtpk(acc[et][4 * i4] * rstd * __uint_as_float(gg.x << 16), acc[et][4 * i4 + 1] * rstd * __uint_as_float(gg.x & 0xffff0000u));
;                   wv.y = cvtpk(acc[et][4 * i4 + 2] * rstd * __uint_as_float(gg.y << 16), acc[et][4 * i4 + 3] * rstd * __uint_as_float(gg.y & 0xffff0000u));
;                   if (!dry || rstd == 1.2345e38f) *(v2u*)p4 = wv; if (i4 == 3 && (et & 1)) asm volatile("" ::: "memory"); } }
	v_permlane32_swap_b32_e32 v204, v206
	v_permlane32_swap_b32_e32 v205, v207
	v_lshlrev_b32_e32 v57, 16, v204
	v_and_b32_e32 v58, 0xffff0000, v204
	v_lshlrev_b32_e32 v59, 16, v205
	v_and_b32_e32 v60, 0xffff0000, v205
	v_mul_f32_e32 v53, v170, v52
	v_mul_f32_e32 v54, v171, v52
	v_mul_f32_e32 v55, v172, v52
	v_mul_f32_e32 v56, v173, v52
	v_mul_f32_e32 v53, v53, v57
	v_mul_f32_e32 v54, v54, v58
	v_mul_f32_e32 v55, v55, v59
	v_mul_f32_e32 v56, v56, v60
	v_cvt_pk_bf16_f32 v250, v53, v54
	v_cvt_pk_bf16_f32 v251, v55, v56
	v_lshlrev_b32_e32 v57, 16, v206
	v_and_b32_e32 v58, 0xffff0000, v206
	v_lshlrev_b32_e32 v59, 16, v207
	v_and_b32_e32 v60, 0xffff0000, v207
	v_mul_f32_e32 v53, v174, v52
	v_mul_f32_e32 v54, v175, v52
	v_mul_f32_e32 v55, v176, v52
	v_mul_f32_e32 v56, v177, v52
	v_mul_f32_e32 v53, v53, v57
	v_mul_f32_e32 v54, v54, v58
	v_mul_f32_e32 v55, v55, v59
	v_mul_f32_e32 v56, v56, v60
	v_cvt_pk_bf16_f32 v252, v53, v54
	v_cvt_pk_bf16_f32 v253, v55, v56
	s_nop 1
	v_permlane32_swap_b32_e32 v250, v252
	v_permlane32_swap_b32_e32 v251, v253
	global_store_dwordx4 v[50:51], v[250:253], off offset:96
	global_load_dwordx4 v[204:207], v[50:51], off offset:480
	s_waitcnt vmcnt(15)
	v_permlane32_swap_b32_e32 v208, v210
	v_permlane32_swap_b32_e32 v209, v211
	v_lshlrev_b32_e32 v57, 16, v208
	v_and_b32_e32 v58, 0xffff0000, v208
	v_lshlrev_b32_e32 v59, 16, v209
	v_and_b32_e32 v60, 0xffff0000, v209
	v_mul_f32_e32 v53, v146, v52
	v_mul_f32_e32 v54, v147, v52
	v_mul_f32_e32 v55, v148, v52
	v_mul_f32_e32 v56, v149, v52
	v_mul_f32_e32 v53, v53, v57
	v_mul_f32_e32 v54, v54, v58
	v_mul_f32_e32 v55, v55, v59
	v_mul_f32_e32 v56, v56, v60
	v_cvt_pk_bf16_f32 v250, v53, v54
	v_cvt_pk_bf16_f32 v251, v55, v56
	v_lshlrev_b32_e32 v57, 16, v210
	v_and_b32_e32 v58, 0xffff0000, v210
	v_lshlrev_b32_e32 v59, 16, v211
	v_and_b32_e32 v60, 0xffff0000, v211
	v_mul_f32_e32 v53, v150, v52
	v_mul_f32_e32 v54, v151, v52
	v_mul_f32_e32 v55, v152, v52
	v_mul_f32_e32 v56, v153, v52
	v_mul_f32_e32 v53, v53, v57
	v_mul_f32_e32 v54, v54, v58
	v_mul_f32_e32 v55, v55, v59
	v_mul_f32_e32 v56, v56, v60
	v_cvt_pk_bf16_f32 v252, v53, v54
	v_cvt_pk_bf16_f32 v253, v55, v56
	s_nop 1
	v_permlane32_swap_b32_e32 v250, v252
	v_permlane32_swap_b32_e32 v251, v253
	global_store_dwordx4 v[50:51], v[250:253], off offset:128
	s_waitcnt vmcnt(15)
	v_permlane32_swap_b32_e32 v212, v214
	v_permlane32_swap_b32_e32 v213, v215
	v_lshlrev_b32_e32 v57, 16, v212
	v_and_b32_e32 v58, 0xffff0000, v212
	v_lshlrev_b32_e32 v59, 16, v213
	v_and_b32_e32 v60, 0xffff0000, v213
	v_mul_f32_e32 v53, v154, v52
	v_mul_f32_e32 v54, v155, v52
	v_mul_f32_e32 v55, v156, v52
	v_mul_f32_e32 v56, v157, v52
	v_mul_f32_e32 v53, v53, v57
	v_mul_f32_e32 v54, v54, v58
	v_mul_f32_e32 v55, v55, v59
	v_mul_f32_e32 v56, v56, v60
	v_cvt_pk_bf16_f32 v250, v53, v54
	v_cvt_pk_bf16_f32 v251, v55, v56
	v_lshlrev_b32_e32 v57, 16, v214
	v_and_b32_e32 v58, 0xffff0000, v214
	v_lshlrev_b32_e32 v59, 16, v215
	v_and_b32_e32 v60, 0xffff0000, v215
	v_mul_f32_e32 v53, v158, v52
	v_mul_f32_e32 v54, v159, v52
	v_mul_f32_e32 v55, v160, v52
	v_mul_f32_e32 v56, v161, v52
	v_mul_f32_e32 v53, v53, v57
	v_mul_f32_e32 v54, v54, v58
	v_mul_f32_e32 v55, v55, v59
	v_mul_f32_e32 v56, v56, v60
	v_cvt_pk_bf16_f32 v252, v53, v54
	v_cvt_pk_bf16_f32 v253, v55, v56
	s_nop 1
	v_permlane32_swap_b32_e32 v250, v252
	v_permlane32_swap_b32_e32 v251, v253
	global_store_dwordx4 v[50:51], v[250:253], off offset:160
	s_waitcnt vmcnt(15)
	v_permlane32_swap_b32_e32 v216, v218
	v_permlane32_swap_b32_e32 v217, v219
	v_lshlrev_b32_e32 v57, 16, v216
	v_and_b32_e32 v58, 0xffff0000, v216
	v_lshlrev_b32_e32 v59, 16, v217
	v_and_b32_e32 v60, 0xffff0000, v217
	v_mul_f32_e32 v53, v130, v52
	v_mul_f32_e32 v54, v131, v52
	v_mul_f32_e32 v55, v132, v52
	v_mul_f32_e32 v56, v133, v52
	v_mul_f32_e32 v53, v53, v57
	v_mul_f32_e32 v54, v54, v58
	v_mul_f32_e32 v55, v55, v59
	v_mul_f32_e32 v56, v56, v60
	v_cvt_pk_bf16_f32 v250, v53, v54
	v_cvt_pk_bf16_f32 v251, v55, v56
	v_lshlrev_b32_e32 v57, 16, v218
	v_and_b32_e32 v58, 0xffff0000, v218
	v_lshlrev_b32_e32 v59, 16, v219
	v_and_b32_e32 v60, 0xffff0000, v219
	v_mul_f32_e32 v53, v134, v52
	v_mul_f32_e32 v54, v135, v52
	v_mul_f32_e32 v55, v136, v52
	v_mul_f32_e32 v56, v137, v52
	v_mul_f32_e32 v53, v53, v57
	v_mul_f32_e32 v54, v54, v58
	v_mul_f32_e32 v55, v55, v59
	v_mul_f32_e32 v56, v56, v60
	v_cvt_pk_bf16_f32 v252, v53, v54
	v_cvt_pk_bf16_f32 v253, v55, v56
	s_nop 1
	v_permlane32_swap_b32_e32 v250, v252
	v_permlane32_swap_b32_e32 v251, v253
	global_store_dwordx4 v[50:51], v[250:253], off offset:192
	s_waitcnt vmcnt(15)
	v_permlane32_swap_b32_e32 v220, v222
	v_permlane32_swap_b32_e32 v221, v223
	v_lshlrev_b32_e32 v57, 16, v220
	v_and_b32_e32 v58, 0xffff0000, v220
	v_lshlrev_b32_e32 v59, 16, v221
	v_and_b32_e32 v60, 0xffff0000, v221
	v_mul_f32_e32 v53, v138, v52
	v_mul_f32_e32 v54, v139, v52
	v_mul_f32_e32 v55, v140, v52
	v_mul_f32_e32 v56, v141, v52
	v_mul_f32_e32 v53, v53, v57
	v_mul_f32_e32 v54, v54, v58
	v_mul_f32_e32 v55, v55, v59
	v_mul_f32_e32 v56, v56, v60
	v_cvt_pk_bf16_f32 v250, v53, v54
	v_cvt_pk_bf16_f32 v251, v55, v56
	v_lshlrev_b32_e32 v57, 16, v222
	v_and_b32_e32 v58, 0xffff0000, v222
	v_lshlrev_b32_e32 v59, 16, v223
	v_and_b32_e32 v60, 0xffff0000, v223
	v_mul_f32_e32 v53, v142, v52
	v_mul_f32_e32 v54, v143, v52
	v_mul_f32_e32 v55, v144, v52
	v_mul_f32_e32 v56, v145, v52
	v_mul_f32_e32 v53, v53, v57
	v_mul_f32_e32 v54, v54, v58
	v_mul_f32_e32 v55, v55, v59
	v_mul_f32_e32 v56, v56, v60
	v_cvt_pk_bf16_f32 v252, v53, v54
	v_cvt_pk_bf16_f32 v253, v55, v56
	s_nop 1
	v_permlane32_swap_b32_e32 v250, v252
	v_permlane32_swap_b32_e32 v251, v253
	global_store_dwordx4 v[50:51], v[250:253], off offset:224
	s_waitcnt vmcnt(15)
; __device__ __forceinline__ unsigned cvtpk(float lo, float hi) { return pg8::cvt_pk_bf16(lo, hi); }
;     ...
;               for (int i4 = 0; i4 < 4; ++i4) { bf16* p4 = gp + 32 * et + 8 * i4; const v2u gg = *(const v2u*)p4;
;                   v2u wv; wv.x = cvtpk(acc[et][4 * i4] * rstd * __uint_as_float(gg.x << 16), acc[et][4 * i4 + 1] * rstd * __uint_as_float(gg.x & 0xffff0000u));
;                   wv.y = cvtpk(acc[et][4 * i4 + 2] * rstd * __uint_as_float(gg.y << 16), acc[et][4 * i4 + 3] * rstd * __uint_as_float(gg.y & 0xffff0000u));
;                   if (!dry || rstd == 1.2345e38f) *(v2u*)p4 = wv; if (i4 == 3 && (et & 1)) asm volatile("" ::: "memory"); } }
	v_permlane32_swap_b32_e32 v224, v226
	v_permlane32_swap_b32_e32 v225, v227
	v_lshlrev_b32_e32 v57, 16, v224
	v_and_b32_e32 v58, 0xffff0000, v224
	v_lshlrev_b32_e32 v59, 16, v225
	v_and_b32_e32 v60, 0xffff0000, v225
	v_mul_f32_e32 v53, v66, v52
	v_mul_f32_e32 v54, v67, v52
	v_mul_f32_e32 v55, v68, v52
	v_mul_f32_e32 v56, v69, v52
	v_mul_f32_e32 v53, v53, v57
	v_mul_f32_e32 v54, v54, v58
	v_mul_f32_e32 v55, v55, v59
	v_mul_f32_e32 v56, v56, v60
	v_cvt_pk_bf16_f32 v250, v53, v54
	v_cvt_pk_bf16_f32 v251, v55, v56
	v_lshlrev_b32_e32 v57, 16, v226
	v_and_b32_e32 v58, 0xffff0000, v226
	v_lshlrev_b32_e32 v59, 16, v227
	v_and_b32_e32 v60, 0xffff0000, v227
	v_mul_f32_e32 v53, v70, v52
	v_mul_f32_e32 v54, v71, v52
	v_mul_f32_e32 v55, v72, v52
	v_mul_f32_e32 v56, v73, v52
	v_mul_f32_e32 v53, v53, v57
	v_mul_f32_e32 v54, v54, v58
	v_mul_f32_e32 v55, v55, v59
	v_mul_f32_e32 v56, v56, v60
	v_cvt_pk_bf16_f32 v252, v53, v54
	v_cvt_pk_bf16_f32 v253, v55, v56
	s_nop 1
	v_permlane32_swap_b32_e32 v250, v252
	v_permlane32_swap_b32_e32 v251, v253
	global_store_dwordx4 v[50:51], v[250:253], off offset:256
	s_waitcnt vmcnt(15)
	v_permlane32_swap_b32_e32 v238, v240
	v_permlane32_swap_b32_e32 v239, v241
	v_lshlrev_b32_e32 v57, 16, v238
	v_and_b32_e32 v58, 0xffff0000, v238
	v_lshlrev_b32_e32 v59, 16, v239
	v_and_b32_e32 v60, 0xffff0000, v239
	v_mul_f32_e32 v53, v74, v52
	v_mul_f32_e32 v54, v75, v52
	v_mul_f32_e32 v55, v76, v52
	v_mul_f32_e32 v56, v77, v52
	v_mul_f32_e32 v53, v53, v57
	v_mul_f32_e32 v54, v54, v58
	v_mul_f32_e32 v55, v55, v59
	v_mul_f32_e32 v56, v56, v60
	v_cvt_pk_bf16_f32 v250, v53, v54
	v_cvt_pk_bf16_f32 v251, v55, v56
	v_lshlrev_b32_e32 v57, 16, v240
	v_and_b32_e32 v58, 0xffff0000, v240
	v_lshlrev_b32_e32 v59, 16, v241
	v_and_b32_e32 v60, 0xffff0000, v241
	v_mul_f32_e32 v53, v78, v52
	v_mul_f32_e32 v54, v79, v52
	v_mul_f32_e32 v55, v80, v52
	v_mul_f32_e32 v56, v81, v52
	v_mul_f32_e32 v53, v53, v57
	v_mul_f32_e32 v54, v54, v58
	v_mul_f32_e32 v55, v55, v59
	v_mul_f32_e32 v56, v56, v60
	v_cvt_pk_bf16_f32 v252, v53, v54
	v_cvt_pk_bf16_f32 v253, v55, v56
	s_nop 1
	v_permlane32_swap_b32_e32 v250, v252
	v_permlane32_swap_b32_e32 v251, v253
	global_store_dwordx4 v[50:51], v[250:253], off offset:288
	s_waitcnt vmcnt(15)
	v_permlane32_swap_b32_e32 v242, v244
	v_permlane32_swap_b32_e32 v243, v245
	v_lshlrev_b32_e32 v57, 16, v242
	v_and_b32_e32 v58, 0xffff0000, v242
	v_lshlrev_b32_e32 v59, 16, v243
	v_and_b32_e32 v60, 0xffff0000, v243
	v_mul_f32_e32 v53, v34, v52
	v_mul_f32_e32 v54, v35, v52
	v_mul_f32_e32 v55, v36, v52
	v_mul_f32_e32 v56, v37, v52
	v_mul_f32_e32 v53, v53, v57
	v_mul_f32_e32 v54, v54, v58
	v_mul_f32_e32 v55, v55, v59
	v_mul_f32_e32 v56, v56, v60
	v_cvt_pk_bf16_f32 v250, v53, v54
	v_cvt_pk_bf16_f32 v251, v55, v56
	v_lshlrev_b32_e32 v57, 16, v244
	v_and_b32_e32 v58, 0xffff0000, v244
	v_lshlrev_b32_e32 v59, 16, v245
	v_and_b32_e32 v60, 0xffff0000, v245
	v_mul_f32_e32 v53, v38, v52
	v_mul_f32_e32 v54, v39, v52
	v_mul_f32_e32 v55, v40, v52
	v_mul_f32_e32 v56, v41, v52
	v_mul_f32_e32 v53, v53, v57
	v_mul_f32_e32 v54, v54, v58
	v_mul_f32_e32 v55, v55, v59
	v_mul_f32_e32 v56, v56, v60
	v_cvt_pk_bf16_f32 v252, v53, v54
	v_cvt_pk_bf16_f32 v253, v55, v56
	s_nop 1
	v_permlane32_swap_b32_e32 v250, v252
	v_permlane32_swap_b32_e32 v251, v253
	global_store_dwordx4 v[50:51], v[250:253], off offset:320
	s_waitcnt vmcnt(15)
	v_permlane32_swap_b32_e32 v246, v248
	v_permlane32_swap_b32_e32 v247, v249
	v_lshlrev_b32_e32 v57, 16, v246
	v_and_b32_e32 v58, 0xffff0000, v246
	v_lshlrev_b32_e32 v59, 16, v247
	v_and_b32_e32 v60, 0xffff0000, v247
	v_mul_f32_e32 v53, v42, v52
	v_mul_f32_e32 v54, v43, v52
	v_mul_f32_e32 v55, v44, v52
	v_mul_f32_e32 v56, v45, v52
	v_mul_f32_e32 v53, v53, v57
	v_mul_f32_e32 v54, v54, v58
	v_mul_f32_e32 v55, v55, v59
	v_mul_f32_e32 v56, v56, v60
	v_cvt_pk_bf16_f32 v250, v53, v54
	v_cvt_pk_bf16_f32 v251, v55, v56
	v_lshlrev_b32_e32 v57, 16, v248
	v_and_b32_e32 v58, 0xffff0000, v248
	v_lshlrev_b32_e32 v59, 16, v249
	v_and_b32_e32 v60, 0xffff0000, v249
	v_mul_f32_e32 v53, v46, v52
	v_mul_f32_e32 v54, v47, v52
	v_mul_f32_e32 v55, v48, v52
	v_mul_f32_e32 v56, v49, v52
	v_mul_f32_e32 v53, v53, v57
	v_mul_f32_e32 v54, v54, v58
	v_mul_f32_e32 v55, v55, v59
	v_mul_f32_e32 v56, v56, v60
	v_cvt_pk_bf16_f32 v252, v53, v54
	v_cvt_pk_bf16_f32 v253, v55, v56
	s_nop 1
	v_permlane32_swap_b32_e32 v250, v252
	v_permlane32_swap_b32_e32 v251, v253
	global_store_dwordx4 v[50:51], v[250:253], off offset:352
	s_waitcnt vmcnt(14)
; __device__ __forceinline__ unsigned cvtpk(float lo, float hi) { return pg8::cvt_pk_bf16(lo, hi); }
;     ...
;         { R2_IDS const float rstd = 1.0f / sqrtf((ssp[32 * nt + r] + ssp[128 + 32 * nt + r]) * (1.0f / 512.0f) + RMS_EPS);
;           bf16* gp = GY + ((size_t)((bh >> 2) * SEQ + tq0 + 32 * nt + r)) * 2048 + h * 512 + 256 * eh + 4 * hh;
; #pragma unroll
;           for (int et = 0; et < 8; ++et)
; #pragma unroll
;               for (int i4 = 0; i4 < 4; ++i4) { bf16* p4 = gp + 32 * et + 8 * i4; const v2u gg = *(const v2u*)p4;
;                   v2u wv; wv.x = cvtpk(acc[et][4 * i4] * rstd * __uint_as_float(gg.x << 16), acc[et][4 * i4 + 1] * rstd * __uint_as_float(gg.x & 0xffff0000u));
;                   wv.y = cvtpk(acc[et][4 * i4 + 2] * rstd * __uint_as_float(gg.y << 16), acc[et][4 * i4 + 3] * rstd * __uint_as_float(gg.y & 0xffff0000u));
;                   if (!dry || rstd == 1.2345e38f) *(v2u*)p4 = wv; if (i4 == 3 && (et & 1)) asm volatile("" ::: "memory"); } }
	v_permlane32_swap_b32_e32 v82, v84
	v_permlane32_swap_b32_e32 v83, v85
	v_lshlrev_b32_e32 v57, 16, v82
	v_and_b32_e32 v58, 0xffff0000, v82
	v_lshlrev_b32_e32 v59, 16, v83
	v_and_b32_e32 v60, 0xffff0000, v83
	v_mul_f32_e32 v53, v16, v52
	v_mul_f32_e32 v54, v17, v52
	v_mul_f32_e32 v55, v18, v52
	v_mul_f32_e32 v56, v19, v52
	v_mul_f32_e32 v53, v53, v57
	v_mul_f32_e32 v54, v54, v58
	v_mul_f32_e32 v55, v55, v59
	v_mul_f32_e32 v56, v56, v60
	v_cvt_pk_bf16_f32 v250, v53, v54
	v_cvt_pk_bf16_f32 v251, v55, v56
	v_lshlrev_b32_e32 v57, 16, v84
	v_and_b32_e32 v58, 0xffff0000, v84
	v_lshlrev_b32_e32 v59, 16, v85
	v_and_b32_e32 v60, 0xffff0000, v85
	v_mul_f32_e32 v53, v20, v52
	v_mul_f32_e32 v54, v21, v52
	v_mul_f32_e32 v55, v22, v52
	v_mul_f32_e32 v56, v23, v52
	v_mul_f32_e32 v53, v53, v57
	v_mul_f32_e32 v54, v54, v58
	v_mul_f32_e32 v55, v55, v59
	v_mul_f32_e32 v56, v56, v60
	v_cvt_pk_bf16_f32 v252, v53, v54
	v_cvt_pk_bf16_f32 v253, v55, v56
	s_nop 1
	v_permlane32_swap_b32_e32 v250, v252
	v_permlane32_swap_b32_e32 v251, v253
	global_store_dwordx4 v[50:51], v[250:253], off offset:384
	s_waitcnt vmcnt(13)
	v_permlane32_swap_b32_e32 v86, v88
	v_permlane32_swap_b32_e32 v87, v89
	v_lshlrev_b32_e32 v57, 16, v86
	v_and_b32_e32 v58, 0xffff0000, v86
	v_lshlrev_b32_e32 v59, 16, v87
	v_and_b32_e32 v60, 0xffff0000, v87
	v_mul_f32_e32 v53, v24, v52
	v_mul_f32_e32 v54, v25, v52
	v_mul_f32_e32 v55, v26, v52
	v_mul_f32_e32 v56, v27, v52
	v_mul_f32_e32 v53, v53, v57
	v_mul_f32_e32 v54, v54, v58
	v_mul_f32_e32 v55, v55, v59
	v_mul_f32_e32 v56, v56, v60
	v_cvt_pk_bf16_f32 v250, v53, v54
	v_cvt_pk_bf16_f32 v251, v55, v56
	v_lshlrev_b32_e32 v57, 16, v88
	v_and_b32_e32 v58, 0xffff0000, v88
	v_lshlrev_b32_e32 v59, 16, v89
	v_and_b32_e32 v60, 0xffff0000, v89
	v_mul_f32_e32 v53, v28, v52
	v_mul_f32_e32 v54, v29, v52
	v_mul_f32_e32 v55, v30, v52
	v_mul_f32_e32 v56, v31, v52
	v_mul_f32_e32 v53, v53, v57
	v_mul_f32_e32 v54, v54, v58
	v_mul_f32_e32 v55, v55, v59
	v_mul_f32_e32 v56, v56, v60
	v_cvt_pk_bf16_f32 v252, v53, v54
	v_cvt_pk_bf16_f32 v253, v55, v56
	s_nop 1
	v_permlane32_swap_b32_e32 v250, v252
	v_permlane32_swap_b32_e32 v251, v253
	global_store_dwordx4 v[50:51], v[250:253], off offset:416
	s_waitcnt vmcnt(12)
	v_permlane32_swap_b32_e32 v90, v92
	v_permlane32_swap_b32_e32 v91, v93
	v_lshlrev_b32_e32 v57, 16, v90
	v_and_b32_e32 v58, 0xffff0000, v90
	v_lshlrev_b32_e32 v59, 16, v91
	v_and_b32_e32 v60, 0xffff0000, v91
	v_mul_f32_e32 v53, v0, v52
	v_mul_f32_e32 v54, v1, v52
	v_mul_f32_e32 v55, v2, v52
	v_mul_f32_e32 v56, v3, v52
	v_mul_f32_e32 v53, v53, v57
	v_mul_f32_e32 v54, v54, v58
	v_mul_f32_e32 v55, v55, v59
	v_mul_f32_e32 v56, v56, v60
	v_cvt_pk_bf16_f32 v250, v53, v54
	v_cvt_pk_bf16_f32 v251, v55, v56
	v_lshlrev_b32_e32 v57, 16, v92
	v_and_b32_e32 v58, 0xffff0000, v92
	v_lshlrev_b32_e32 v59, 16, v93
	v_and_b32_e32 v60, 0xffff0000, v93
	v_mul_f32_e32 v53, v4, v52
	v_mul_f32_e32 v54, v5, v52
	v_mul_f32_e32 v55, v6, v52
	v_mul_f32_e32 v56, v7, v52
	v_mul_f32_e32 v53, v53, v57
	v_mul_f32_e32 v54, v54, v58
	v_mul_f32_e32 v55, v55, v59
	v_mul_f32_e32 v56, v56, v60
	v_cvt_pk_bf16_f32 v252, v53, v54
	v_cvt_pk_bf16_f32 v253, v55, v56
	s_nop 1
	v_permlane32_swap_b32_e32 v250, v252
	v_permlane32_swap_b32_e32 v251, v253
	global_store_dwordx4 v[50:51], v[250:253], off offset:448
	s_waitcnt vmcnt(11)
	v_permlane32_swap_b32_e32 v204, v206
	v_permlane32_swap_b32_e32 v205, v207
	v_lshlrev_b32_e32 v57, 16, v204
	v_and_b32_e32 v58, 0xffff0000, v204
	v_lshlrev_b32_e32 v59, 16, v205
	v_and_b32_e32 v60, 0xffff0000, v205
	v_mul_f32_e32 v53, v8, v52
	v_mul_f32_e32 v54, v9, v52
	v_mul_f32_e32 v55, v10, v52
	v_mul_f32_e32 v56, v11, v52
	v_mul_f32_e32 v53, v53, v57
	v_mul_f32_e32 v54, v54, v58
	v_mul_f32_e32 v55, v55, v59
	v_mul_f32_e32 v56, v56, v60
	v_cvt_pk_bf16_f32 v250, v53, v54
	v_cvt_pk_bf16_f32 v251, v55, v56
	v_lshlrev_b32_e32 v57, 16, v206
	v_and_b32_e32 v58, 0xffff0000, v206
	v_lshlrev_b32_e32 v59, 16, v207
	v_and_b32_e32 v60, 0xffff0000, v207
	v_mul_f32_e32 v53, v12, v52
	v_mul_f32_e32 v54, v13, v52
	v_mul_f32_e32 v55, v14, v52
	v_mul_f32_e32 v56, v15, v52
	v_mul_f32_e32 v53, v53, v57
	v_mul_f32_e32 v54, v54, v58
	v_mul_f32_e32 v55, v55, v59
	v_mul_f32_e32 v56, v56, v60
	v_cvt_pk_bf16_f32 v252, v53, v54
	v_cvt_pk_bf16_f32 v253, v55, v56
	s_nop 1
	v_permlane32_swap_b32_e32 v250, v252
	v_permlane32_swap_b32_e32 v251, v253
	global_store_dwordx4 v[50:51], v[250:253], off offset:480
	s_cbranch_scc0 .LBB0_734
